# epilogue de-serialisation also in the mixer out-proj epilogue (three of four second-half row groups hoisted)
# baseline (speedup 1.0000x reference)
; __device__ __forceinline__ u32x4 pack8(f32x4 a, f32x4 b) { u32x4 w; w.x = cvtpk(a[0], a[1]); w.y = cvtpk(a[2], a[3]); w.z = cvtpk(b[0], b[1]); w.w = cvtpk(b[2], b[3]); return w; }
;     __device__ __forceinline__ void operator()(AccRef acc, const Unit& u, int wr, int wc, int fr, int fq) const {
;     ...
;         for (int ai = 0; ai < 2; ++ai) {
;             u32x4 ow[4][2];
; #pragma unroll
;             for (int m = 0; m < 4; ++m)
; #pragma unroll
;                 for (int bj = 0; bj < 2; ++bj)
;                     ow[m][bj] = *(const u32x4*)(hb + (size_t)(u.pm * 256 + ai * 128 + wr * 64 + m * 16 + fr) * D + u.pn * 256 + bj * 128 + wc * 32 + 8 * fq);
;             __builtin_amdgcn_sched_barrier(0);
; #pragma unroll
;             for (int m = 0; m < 4; ++m) {
;                 const int row = u.pm * 256 + ai * 128 + wr * 64 + m * 16 + fr; float part = 0.f;
;                 const float sc = RS ? scale * rst[u.ui * 256 + ai * 128 + wr * 64 + m * 16 + fr] : scale;
; #pragma unroll
;                 for (int bj = 0; bj < 2; ++bj) {
;                     const size_t idx = (size_t)row * D + u.pn * 256 + bj * 128 + wc * 32 + 8 * fq;
;                     const u32x4 o4 = ow[m][bj];
;                     f32x4 v0, v1;
;                     v0[0] = __uint_as_float(o4.x << 16); v0[1] = __uint_as_float(o4.x & 0xffff0000u); v0[2] = __uint_as_float(o4.y << 16); v0[3] = __uint_as_float(o4.y & 0xffff0000u);
;                     v1[0] = __uint_as_float(o4.z << 16); v1[1] = __uint_as_float(o4.z & 0xffff0000u); v1[2] = __uint_as_float(o4.w << 16); v1[3] = __uint_as_float(o4.w & 0xffff0000u);
;                     v0 = v0 + acc[ai][bj][m][0] * sc; v1 = v1 + acc[ai][bj][m][1] * sc;
;                     *(u32x4*)(hb + idx) = pack8(v0, v1);
;                     part += (v0[0] * v0[0] + v0[1] * v0[1]) + (v0[2] * v0[2] + v0[3] * v0[3]) + (v1[0] * v1[0] + v1[1] * v1[1]) + (v1[2] * v1[2] + v1[3] * v1[3]);
;                 }
;                 part = fq_sum(part);
;                 if (fq == 0) ssn[(size_t)row * 16 + u.pn * 4 + wc] = part;
;             }
.LBB0_1504:
	v_mov_b32_e32 v0, v236
	s_lshl_b32 s62, s5, 8
	s_ashr_i32 s63, s62, 31
	v_and_b32_e32 v155, 15, v0
	v_bfe_u32 v157, v0, 4, 2
	v_or_b32_e32 v0, s69, v155
	s_lshl_b64 s[64:65], s[62:63], 1
	v_lshl_add_u32 v162, s4, 8, v0
	s_add_u32 s66, s75, s64
	s_addc_u32 s67, s76, s65
	v_lshlrev_b32_e32 v0, 4, v157
	v_ashrrev_i32_e32 v163, 31, v162
	v_or_b32_e32 v174, 16, v162
	v_lshl_add_u64 v[164:165], s[66:67], 0, v[0:1]
	v_lshlrev_b64 v[188:189], 11, v[162:163]
	v_ashrrev_i32_e32 v175, 31, v174
	v_or_b32_e32 v170, 32, v162
	v_lshl_add_u64 v[130:131], v[164:165], 0, v[188:189]
	v_lshlrev_b64 v[176:177], 11, v[174:175]
	v_ashrrev_i32_e32 v171, 31, v170
	v_or_b32_e32 v166, 48, v162
	global_load_dwordx4 v[180:183], v[130:131], off
	global_load_dwordx4 v[184:187], v[130:131], off offset:256
	v_lshl_add_u64 v[130:131], v[164:165], 0, v[176:177]
	v_lshlrev_b64 v[172:173], 11, v[170:171]
	v_ashrrev_i32_e32 v167, 31, v166
	global_load_dwordx4 v[150:153], v[130:131], off
	global_load_dwordx4 v[146:149], v[130:131], off offset:256
	v_lshl_add_u64 v[130:131], v[164:165], 0, v[172:173]
	v_lshlrev_b64 v[168:169], 11, v[166:167]
	global_load_dwordx4 v[142:145], v[130:131], off
	global_load_dwordx4 v[138:141], v[130:131], off offset:256
	v_lshl_add_u64 v[130:131], v[164:165], 0, v[168:169]
	global_load_dwordx4 v[134:137], v[130:131], off
	s_nop 0
	global_load_dwordx4 v[130:133], v[130:131], off offset:256
	v_mov_b32_e32 v190, 0x40000
	v_mov_b32_e32 v191, 0
	v_lshl_add_u64 v[204:205], v[190:191], 0, v[188:189]
	v_lshl_add_u64 v[204:205], v[164:165], 0, v[204:205]
	global_load_dwordx4 v[208:211], v[204:205], off
	global_load_dwordx4 v[212:215], v[204:205], off offset:256
	v_lshl_add_u64 v[204:205], v[190:191], 0, v[176:177]
	v_lshl_add_u64 v[204:205], v[164:165], 0, v[204:205]
	global_load_dwordx4 v[220:223], v[204:205], off
	global_load_dwordx4 v[238:241], v[204:205], off offset:256
	v_lshl_add_u64 v[204:205], v[190:191], 0, v[172:173]
	v_lshl_add_u64 v[204:205], v[164:165], 0, v[204:205]
	global_load_dwordx4 v[242:245], v[204:205], off
	global_load_dwordx4 v[250:253], v[204:205], off offset:256
	v_cmp_eq_u32_e32 vcc, 0, v157
	s_lshl_b32 s18, s80, 10
	s_add_i32 s18, s77, s18
	v_lshl_add_u32 v155, v155, 2, s18
	ds_read_b32 v196, v155
	v_lshl_add_u64 v[188:189], s[12:13], 0, v[188:189]
	s_waitcnt vmcnt(0)
	v_lshlrev_b32_e32 v198, 16, v180
	v_and_b32_e32 v199, 0xffff0000, v180
	v_lshlrev_b32_e32 v180, 16, v181
	v_and_b32_e32 v181, 0xffff0000, v181
	v_lshl_add_u64 v[188:189], v[188:189], 0, s[64:65]
	s_lshl_b32 s18, s71, 1
	s_waitcnt lgkmcnt(0)
	v_pk_fma_f32 v[202:203], v[128:129], v[196:197], v[180:181] op_sel_hi:[1,0,1]
	v_pk_fma_f32 v[198:199], v[126:127], v[196:197], v[198:199] op_sel_hi:[1,0,1]
	v_lshl_add_u64 v[188:189], v[188:189], 0, s[18:19]
	v_lshlrev_b32_e32 v200, 16, v182
	v_and_b32_e32 v201, 0xffff0000, v182
	v_lshl_add_u64 v[188:189], v[188:189], 0, v[0:1]
	v_mul_f32_e32 v0, v199, v199
	v_mul_f32_e32 v159, v203, v203
	v_lshlrev_b32_e32 v182, 16, v183
	v_and_b32_e32 v183, 0xffff0000, v183
	v_pk_fma_f32 v[200:201], v[122:123], v[196:197], v[200:201] op_sel_hi:[1,0,1]
	v_fmac_f32_e32 v0, v198, v198
	v_fmac_f32_e32 v159, v202, v202
	v_pk_fma_f32 v[206:207], v[124:125], v[196:197], v[182:183] op_sel_hi:[1,0,1]
	v_add_f32_e32 v0, v0, v159
	v_mul_f32_e32 v159, v201, v201
	v_cvt_pk_bf16_f32 v180, v198, v199
	v_cvt_pk_bf16_f32 v181, v202, v203
	v_cvt_pk_bf16_f32 v182, v200, v201
	v_cvt_pk_bf16_f32 v183, v206, v207
	v_fmac_f32_e32 v159, v200, v200
	global_store_dwordx4 v[188:189], v[180:183], off
	v_add_f32_e32 v0, v159, v0
	v_mul_f32_e32 v159, v207, v207
	v_lshlrev_b32_e32 v180, 16, v184
	v_and_b32_e32 v181, 0xffff0000, v184
	v_lshlrev_b32_e32 v182, 16, v185
	v_and_b32_e32 v183, 0xffff0000, v185
	v_fmac_f32_e32 v159, v206, v206
	v_pk_fma_f32 v[198:199], v[96:97], v[196:197], v[182:183] op_sel_hi:[1,0,1]
	v_pk_fma_f32 v[200:201], v[94:95], v[196:197], v[180:181] op_sel_hi:[1,0,1]
	v_add_f32_e32 v0, v159, v0
	v_lshlrev_b32_e32 v184, 16, v186
	v_and_b32_e32 v185, 0xffff0000, v186
	v_mul_f32_e32 v159, v201, v201
	v_mul_f32_e32 v161, v199, v199
	v_pk_fma_f32 v[184:185], v[90:91], v[196:197], v[184:185] op_sel_hi:[1,0,1]
	v_fmac_f32_e32 v159, v200, v200
	v_fmac_f32_e32 v161, v198, v198
	v_lshlrev_b32_e32 v186, 16, v187
	v_and_b32_e32 v187, 0xffff0000, v187
	v_add_f32_e32 v159, v159, v161
	v_mul_f32_e32 v161, v185, v185
	v_pk_fma_f32 v[186:187], v[92:93], v[196:197], v[186:187] op_sel_hi:[1,0,1]
	v_fmac_f32_e32 v161, v184, v184
	v_add_f32_e32 v159, v161, v159
	v_mul_f32_e32 v161, v187, v187
	v_fmac_f32_e32 v161, v186, v186
	v_add_f32_e32 v159, v161, v159
	v_add_f32_e32 v0, v0, v159
	v_mov_b32_e32 v159, v0
	s_nop 1
	v_permlane32_swap_b32_e32 v0, v159
	v_add_f32_e32 v0, v0, v159
	v_mov_b32_e32 v159, v0
	v_cvt_pk_bf16_f32 v180, v200, v201
	v_cvt_pk_bf16_f32 v181, v198, v199
	v_cvt_pk_bf16_f32 v182, v184, v185
	v_cvt_pk_bf16_f32 v183, v186, v187
	v_permlane16_swap_b32_e32 v0, v159
	global_store_dwordx4 v[188:189], v[180:183], off offset:256
	s_and_saveexec_b64 s[64:65], vcc
	s_cbranch_execz .LBB0_1506
	s_lshl_b32 s66, s5, 2
	v_lshlrev_b64 v[180:181], 6, v[162:163]
	s_ashr_i32 s67, s66, 31
	v_lshl_add_u64 v[180:181], s[14:15], 0, v[180:181]
	v_lshl_add_u64 v[180:181], s[66:67], 2, v[180:181]
	s_lshl_b32 s66, s68, 2
	s_mov_b32 s67, s19
	v_add_f32_e32 v0, v0, v159
	v_lshl_add_u64 v[180:181], v[180:181], 0, s[66:67]
	global_store_dword v[180:181], v0, off

; __device__ __forceinline__ u32x4 pack8(f32x4 a, f32x4 b) { u32x4 w; w.x = cvtpk(a[0], a[1]); w.y = cvtpk(a[2], a[3]); w.z = cvtpk(b[0], b[1]); w.w = cvtpk(b[2], b[3]); return w; }
;     __device__ __forceinline__ void operator()(AccRef acc, const Unit& u, int wr, int wc, int fr, int fq) const {
;     ...
;         for (int ai = 0; ai < 2; ++ai) {
;             u32x4 ow[4][2];
; #pragma unroll
;             for (int m = 0; m < 4; ++m)
; #pragma unroll
;                 for (int bj = 0; bj < 2; ++bj)
;                     ow[m][bj] = *(const u32x4*)(hb + (size_t)(u.pm * 256 + ai * 128 + wr * 64 + m * 16 + fr) * D + u.pn * 256 + bj * 128 + wc * 32 + 8 * fq);
;             __builtin_amdgcn_sched_barrier(0);
; #pragma unroll
;             for (int m = 0; m < 4; ++m) {
;                 const int row = u.pm * 256 + ai * 128 + wr * 64 + m * 16 + fr; float part = 0.f;
;                 const float sc = RS ? scale * rst[u.ui * 256 + ai * 128 + wr * 64 + m * 16 + fr] : scale;
; #pragma unroll
;                 for (int bj = 0; bj < 2; ++bj) {
;                     const size_t idx = (size_t)row * D + u.pn * 256 + bj * 128 + wc * 32 + 8 * fq;
;                     const u32x4 o4 = ow[m][bj];
;                     f32x4 v0, v1;
;                     v0[0] = __uint_as_float(o4.x << 16); v0[1] = __uint_as_float(o4.x & 0xffff0000u); v0[2] = __uint_as_float(o4.y << 16); v0[3] = __uint_as_float(o4.y & 0xffff0000u);
;                     v1[0] = __uint_as_float(o4.z << 16); v1[1] = __uint_as_float(o4.z & 0xffff0000u); v1[2] = __uint_as_float(o4.w << 16); v1[3] = __uint_as_float(o4.w & 0xffff0000u);
;                     v0 = v0 + acc[ai][bj][m][0] * sc; v1 = v1 + acc[ai][bj][m][1] * sc;
;                     *(u32x4*)(hb + idx) = pack8(v0, v1);
;                     part += (v0[0] * v0[0] + v0[1] * v0[1]) + (v0[2] * v0[2] + v0[3] * v0[3]) + (v1[0] * v1[0] + v1[1] * v1[1]) + (v1[2] * v1[2] + v1[3] * v1[3]);
;                 }
;                 part = fq_sum(part);
;                 if (fq == 0) ssn[(size_t)row * 16 + u.pn * 4 + wc] = part;
;             }
.LBB0_1512:
	s_or_b64 exec, exec, s[64:65]
	v_add_u32_e32 v172, 0x80, v162
	v_ashrrev_i32_e32 v173, 31, v172
	v_add_u32_e32 v168, 0x90, v162
	v_lshlrev_b64 v[184:185], 11, v[172:173]
	v_ashrrev_i32_e32 v169, 31, v168
	v_lshl_add_u64 v[130:131], v[164:165], 0, v[184:185]
	v_lshlrev_b64 v[170:171], 11, v[168:169]
	v_add_u32_e32 v166, 0xa0, v162
	v_lshl_add_u64 v[130:131], v[164:165], 0, v[170:171]
	v_ashrrev_i32_e32 v167, 31, v166
	v_lshlrev_b64 v[130:131], 11, v[166:167]
	v_add_u32_e32 v162, 0xb0, v162
	v_lshl_add_u64 v[130:131], v[164:165], 0, v[130:131]
	v_ashrrev_i32_e32 v163, 31, v162
	v_lshlrev_b64 v[130:131], 11, v[162:163]
	v_lshl_add_u64 v[130:131], v[164:165], 0, v[130:131]
	global_load_dwordx4 v[134:137], v[130:131], off
	s_nop 0
	global_load_dwordx4 v[130:133], v[130:131], off offset:256
	ds_read_b32 v164, v155 offset:512
	s_waitcnt vmcnt(7)
	v_lshlrev_b32_e32 v186, 16, v208
	v_and_b32_e32 v187, 0xffff0000, v208
	v_lshlrev_b32_e32 v174, 16, v209
	v_and_b32_e32 v175, 0xffff0000, v209
	s_waitcnt lgkmcnt(0)
	v_pk_fma_f32 v[196:197], v[64:65], v[164:165], v[174:175] op_sel_hi:[1,0,1]
	v_pk_fma_f32 v[186:187], v[62:63], v[164:165], v[186:187] op_sel_hi:[1,0,1]
	v_lshlrev_b32_e32 v188, 16, v210
	v_and_b32_e32 v189, 0xffff0000, v210
	v_lshl_add_u64 v[184:185], s[12:13], 0, v[184:185]
	v_mul_f32_e32 v157, v187, v187
	v_mul_f32_e32 v159, v197, v197
	v_lshlrev_b32_e32 v176, 16, v211
	v_and_b32_e32 v177, 0xffff0000, v211
	v_pk_fma_f32 v[188:189], v[58:59], v[164:165], v[188:189] op_sel_hi:[1,0,1]
	v_lshl_add_u64 v[184:185], s[62:63], 1, v[184:185]
	v_fmac_f32_e32 v157, v186, v186
	v_fmac_f32_e32 v159, v196, v196
	v_pk_fma_f32 v[198:199], v[60:61], v[164:165], v[176:177] op_sel_hi:[1,0,1]
	v_lshl_add_u64 v[184:185], v[184:185], 0, s[18:19]
	v_add_f32_e32 v157, v157, v159
	v_mul_f32_e32 v159, v189, v189
	v_cvt_pk_bf16_f32 v174, v186, v187
	v_cvt_pk_bf16_f32 v175, v196, v197
	v_cvt_pk_bf16_f32 v176, v188, v189
	v_cvt_pk_bf16_f32 v177, v198, v199
	v_lshl_add_u64 v[184:185], v[184:185], 0, v[0:1]
	v_fmac_f32_e32 v159, v188, v188
	global_store_dwordx4 v[184:185], v[174:177], off
	v_add_f32_e32 v157, v159, v157
	v_mul_f32_e32 v159, v199, v199
	s_waitcnt vmcnt(7)
	v_lshlrev_b32_e32 v174, 16, v212
	v_and_b32_e32 v175, 0xffff0000, v212
	v_lshlrev_b32_e32 v176, 16, v213
	v_and_b32_e32 v177, 0xffff0000, v213
	v_fmac_f32_e32 v159, v198, v198
	v_pk_fma_f32 v[186:187], v[32:33], v[164:165], v[176:177] op_sel_hi:[1,0,1]
	v_pk_fma_f32 v[188:189], v[30:31], v[164:165], v[174:175] op_sel_hi:[1,0,1]
	v_add_f32_e32 v157, v159, v157
	v_lshlrev_b32_e32 v180, 16, v214
	v_and_b32_e32 v181, 0xffff0000, v214
	v_lshlrev_b32_e32 v182, 16, v215
	v_and_b32_e32 v183, 0xffff0000, v215
	v_mul_f32_e32 v159, v189, v189
	v_mul_f32_e32 v161, v187, v187
	v_pk_fma_f32 v[182:183], v[28:29], v[164:165], v[182:183] op_sel_hi:[1,0,1]
	v_pk_fma_f32 v[164:165], v[26:27], v[164:165], v[180:181] op_sel_hi:[1,0,1]
	v_fmac_f32_e32 v159, v188, v188
	v_fmac_f32_e32 v161, v186, v186
	v_add_f32_e32 v159, v159, v161
	v_mul_f32_e32 v161, v165, v165
	v_fmac_f32_e32 v161, v164, v164
	v_add_f32_e32 v159, v161, v159
	v_mul_f32_e32 v161, v183, v183
	v_fmac_f32_e32 v161, v182, v182
	v_add_f32_e32 v159, v161, v159
	v_add_f32_e32 v157, v157, v159
	v_mov_b32_e32 v159, v157
	s_nop 1
	v_permlane32_swap_b32_e32 v157, v159
	v_add_f32_e32 v157, v157, v159
	v_mov_b32_e32 v159, v157
	v_cvt_pk_bf16_f32 v174, v188, v189
	v_cvt_pk_bf16_f32 v175, v186, v187
	v_cvt_pk_bf16_f32 v176, v164, v165
	v_cvt_pk_bf16_f32 v177, v182, v183
	v_permlane16_swap_b32_e32 v157, v159
	global_store_dwordx4 v[184:185], v[174:177], off offset:256
	s_and_saveexec_b64 s[64:65], vcc
	s_cbranch_execz .LBB0_1514
	s_lshl_b32 s66, s5, 2
	v_lshlrev_b64 v[164:165], 6, v[172:173]
	s_ashr_i32 s67, s66, 31
	v_lshl_add_u64 v[164:165], s[14:15], 0, v[164:165]
	v_lshl_add_u64 v[164:165], s[66:67], 2, v[164:165]
	s_lshl_b32 s66, s68, 2
	s_mov_b32 s67, s19
	v_add_f32_e32 v157, v157, v159
	v_lshl_add_u64 v[164:165], v[164:165], 0, s[66:67]
	global_store_dword v[164:165], v157, off
; __device__ __forceinline__ u32x4 pack8(f32x4 a, f32x4 b) { u32x4 w; w.x = cvtpk(a[0], a[1]); w.y = cvtpk(a[2], a[3]); w.z = cvtpk(b[0], b[1]); w.w = cvtpk(b[2], b[3]); return w; }
;     __device__ __forceinline__ void operator()(AccRef acc, const Unit& u, int wr, int wc, int fr, int fq) const {
;     ...
;             for (int m = 0; m < 4; ++m) {
;                 const int row = u.pm * 256 + ai * 128 + wr * 64 + m * 16 + fr; float part = 0.f;
;                 const float sc = RS ? scale * rst[u.ui * 256 + ai * 128 + wr * 64 + m * 16 + fr] : scale;
; #pragma unroll
;                 for (int bj = 0; bj < 2; ++bj) {
;                     const size_t idx = (size_t)row * D + u.pn * 256 + bj * 128 + wc * 32 + 8 * fq;
;                     const u32x4 o4 = ow[m][bj];
;                     f32x4 v0, v1;
;                     v0[0] = __uint_as_float(o4.x << 16); v0[1] = __uint_as_float(o4.x & 0xffff0000u); v0[2] = __uint_as_float(o4.y << 16); v0[3] = __uint_as_float(o4.y & 0xffff0000u);
;                     v1[0] = __uint_as_float(o4.z << 16); v1[1] = __uint_as_float(o4.z & 0xffff0000u); v1[2] = __uint_as_float(o4.w << 16); v1[3] = __uint_as_float(o4.w & 0xffff0000u);
;                     v0 = v0 + acc[ai][bj][m][0] * sc; v1 = v1 + acc[ai][bj][m][1] * sc;
;                     *(u32x4*)(hb + idx) = pack8(v0, v1);
;                     part += (v0[0] * v0[0] + v0[1] * v0[1]) + (v0[2] * v0[2] + v0[3] * v0[3]) + (v1[0] * v1[0] + v1[1] * v1[1]) + (v1[2] * v1[2] + v1[3] * v1[3]);
;                 }
;                 part = fq_sum(part);
;                 if (fq == 0) ssn[(size_t)row * 16 + u.pn * 4 + wc] = part;
;             }
.LBB0_1514:
	s_or_b64 exec, exec, s[64:65]
	ds_read_b32 v164, v155 offset:576
	v_lshl_add_u64 v[170:171], s[12:13], 0, v[170:171]
	s_waitcnt vmcnt(7)
	v_lshlrev_b32_e32 v172, 16, v220
	v_and_b32_e32 v173, 0xffff0000, v220
	v_lshlrev_b32_e32 v150, 16, v221
	v_and_b32_e32 v151, 0xffff0000, v221
	v_lshlrev_b32_e32 v174, 16, v222
	v_and_b32_e32 v175, 0xffff0000, v222
	v_lshlrev_b32_e32 v152, 16, v223
	v_and_b32_e32 v153, 0xffff0000, v223
	v_lshl_add_u64 v[170:171], s[62:63], 1, v[170:171]
	s_waitcnt lgkmcnt(0)
	v_pk_fma_f32 v[176:177], v[56:57], v[164:165], v[150:151] op_sel_hi:[1,0,1]
	v_pk_fma_f32 v[172:173], v[54:55], v[164:165], v[172:173] op_sel_hi:[1,0,1]
	v_pk_fma_f32 v[180:181], v[52:53], v[164:165], v[152:153] op_sel_hi:[1,0,1]
	v_pk_fma_f32 v[174:175], v[50:51], v[164:165], v[174:175] op_sel_hi:[1,0,1]
	v_lshl_add_u64 v[170:171], v[170:171], 0, s[18:19]
	v_cvt_pk_bf16_f32 v150, v172, v173
	v_cvt_pk_bf16_f32 v151, v176, v177
	v_cvt_pk_bf16_f32 v152, v174, v175
	v_cvt_pk_bf16_f32 v153, v180, v181
	v_lshl_add_u64 v[170:171], v[170:171], 0, v[0:1]
	global_store_dwordx4 v[170:171], v[150:153], off
	s_nop 1
	v_mul_f32_e32 v150, v173, v173
	v_mul_f32_e32 v151, v177, v177
	v_fmac_f32_e32 v150, v172, v172
	v_fmac_f32_e32 v151, v176, v176
	v_add_f32_e32 v150, v150, v151
	v_mul_f32_e32 v151, v175, v175
	v_fmac_f32_e32 v151, v174, v174
	v_add_f32_e32 v150, v151, v150
	v_mul_f32_e32 v151, v181, v181
	v_fmac_f32_e32 v151, v180, v180
	v_add_f32_e32 v157, v151, v150
	s_waitcnt vmcnt(7)
	v_lshlrev_b32_e32 v150, 16, v238
	v_and_b32_e32 v151, 0xffff0000, v238
	v_lshlrev_b32_e32 v146, 16, v239
	v_and_b32_e32 v147, 0xffff0000, v239
	v_lshlrev_b32_e32 v152, 16, v240
	v_and_b32_e32 v153, 0xffff0000, v240
	v_lshlrev_b32_e32 v148, 16, v241
	v_and_b32_e32 v149, 0xffff0000, v241
	v_pk_fma_f32 v[172:173], v[24:25], v[164:165], v[146:147] op_sel_hi:[1,0,1]
	v_pk_fma_f32 v[150:151], v[22:23], v[164:165], v[150:151] op_sel_hi:[1,0,1]
	v_pk_fma_f32 v[174:175], v[20:21], v[164:165], v[148:149] op_sel_hi:[1,0,1]
	v_pk_fma_f32 v[152:153], v[18:19], v[164:165], v[152:153] op_sel_hi:[1,0,1]
	v_cvt_pk_bf16_f32 v146, v150, v151
	v_cvt_pk_bf16_f32 v147, v172, v173
	v_cvt_pk_bf16_f32 v148, v152, v153
	v_cvt_pk_bf16_f32 v149, v174, v175
	global_store_dwordx4 v[170:171], v[146:149], off offset:256
	s_nop 1
	v_mul_f32_e32 v146, v151, v151
	v_mul_f32_e32 v147, v173, v173
	v_fmac_f32_e32 v146, v150, v150
	v_fmac_f32_e32 v147, v172, v172
	v_add_f32_e32 v146, v146, v147
	v_mul_f32_e32 v147, v153, v153
	v_fmac_f32_e32 v147, v152, v152
	v_add_f32_e32 v146, v147, v146
	v_mul_f32_e32 v147, v175, v175
	v_fmac_f32_e32 v147, v174, v174
	v_add_f32_e32 v146, v147, v146
	v_add_f32_e32 v146, v157, v146
	v_mov_b32_e32 v147, v146
	s_nop 1
	v_permlane32_swap_b32_e32 v146, v147
	v_add_f32_e32 v146, v146, v147
	v_mov_b32_e32 v147, v146
	s_nop 1
	v_permlane16_swap_b32_e32 v146, v147
	s_and_saveexec_b64 s[64:65], vcc
	s_cbranch_execz .LBB0_1516
	v_add_f32_e32 v148, v146, v147
	s_lshl_b32 s66, s5, 2
	v_lshlrev_b64 v[146:147], 6, v[168:169]
	s_ashr_i32 s67, s66, 31
	v_lshl_add_u64 v[146:147], s[14:15], 0, v[146:147]
	v_lshl_add_u64 v[146:147], s[66:67], 2, v[146:147]
	s_lshl_b32 s66, s68, 2
	s_mov_b32 s67, s19
	v_lshl_add_u64 v[146:147], v[146:147], 0, s[66:67]
	global_store_dword v[146:147], v148, off
.LBB0_1516:
	s_or_b64 exec, exec, s[64:65]
	ds_read_b32 v146, v155 offset:640
	v_lshlrev_b64 v[148:149], 11, v[166:167]
	v_lshl_add_u64 v[148:149], s[12:13], 0, v[148:149]
	s_waitcnt vmcnt(7)
	v_lshlrev_b32_e32 v150, 16, v242
	v_and_b32_e32 v151, 0xffff0000, v242
	v_lshlrev_b32_e32 v142, 16, v243
	v_and_b32_e32 v143, 0xffff0000, v243
	v_lshlrev_b32_e32 v152, 16, v244
	v_and_b32_e32 v153, 0xffff0000, v244
	v_lshlrev_b32_e32 v144, 16, v245
	v_and_b32_e32 v145, 0xffff0000, v245
	v_lshl_add_u64 v[148:149], s[62:63], 1, v[148:149]
	s_waitcnt lgkmcnt(0)
	v_pk_fma_f32 v[164:165], v[48:49], v[146:147], v[142:143] op_sel_hi:[1,0,1]
	v_pk_fma_f32 v[150:151], v[46:47], v[146:147], v[150:151] op_sel_hi:[1,0,1]
	v_pk_fma_f32 v[168:169], v[44:45], v[146:147], v[144:145] op_sel_hi:[1,0,1]
	v_pk_fma_f32 v[152:153], v[42:43], v[146:147], v[152:153] op_sel_hi:[1,0,1]
	v_lshl_add_u64 v[148:149], v[148:149], 0, s[18:19]
	v_cvt_pk_bf16_f32 v142, v150, v151
	v_cvt_pk_bf16_f32 v143, v164, v165
	v_cvt_pk_bf16_f32 v144, v152, v153
	v_cvt_pk_bf16_f32 v145, v168, v169
	v_lshl_add_u64 v[148:149], v[148:149], 0, v[0:1]
	global_store_dwordx4 v[148:149], v[142:145], off
	s_nop 1
	v_mul_f32_e32 v142, v151, v151
	v_mul_f32_e32 v143, v165, v165
	v_fmac_f32_e32 v142, v150, v150
	v_fmac_f32_e32 v143, v164, v164
	v_add_f32_e32 v142, v142, v143
	v_mul_f32_e32 v143, v153, v153
	v_fmac_f32_e32 v143, v152, v152
	v_add_f32_e32 v142, v143, v142
	v_mul_f32_e32 v143, v169, v169
	v_fmac_f32_e32 v143, v168, v168
	v_add_f32_e32 v147, v143, v142
	s_waitcnt vmcnt(7)
	v_lshlrev_b32_e32 v142, 16, v250
	v_and_b32_e32 v143, 0xffff0000, v250
	v_lshlrev_b32_e32 v138, 16, v251
	v_and_b32_e32 v139, 0xffff0000, v251
	v_lshlrev_b32_e32 v144, 16, v252
	v_and_b32_e32 v145, 0xffff0000, v252
	v_lshlrev_b32_e32 v140, 16, v253
	v_and_b32_e32 v141, 0xffff0000, v253
	v_pk_fma_f32 v[150:151], v[16:17], v[146:147], v[138:139] op_sel_hi:[1,0,1]
	v_pk_fma_f32 v[142:143], v[14:15], v[146:147], v[142:143] op_sel_hi:[1,0,1]
	v_pk_fma_f32 v[152:153], v[12:13], v[146:147], v[140:141] op_sel_hi:[1,0,1]
	v_pk_fma_f32 v[144:145], v[10:11], v[146:147], v[144:145] op_sel_hi:[1,0,1]
	v_cvt_pk_bf16_f32 v138, v142, v143
	v_cvt_pk_bf16_f32 v139, v150, v151
	v_cvt_pk_bf16_f32 v140, v144, v145
	v_cvt_pk_bf16_f32 v141, v152, v153
	global_store_dwordx4 v[148:149], v[138:141], off offset:256
	s_nop 1
	v_mul_f32_e32 v138, v143, v143
	v_mul_f32_e32 v139, v151, v151
	v_fmac_f32_e32 v138, v142, v142
	v_fmac_f32_e32 v139, v150, v150
	v_add_f32_e32 v138, v138, v139
	v_mul_f32_e32 v139, v145, v145
	v_fmac_f32_e32 v139, v144, v144
	v_add_f32_e32 v138, v139, v138
	v_mul_f32_e32 v139, v153, v153
	v_fmac_f32_e32 v139, v152, v152
	v_add_f32_e32 v138, v139, v138
	v_add_f32_e32 v138, v147, v138
	v_mov_b32_e32 v139, v138
	s_nop 1
	v_permlane32_swap_b32_e32 v138, v139
	v_add_f32_e32 v138, v138, v139
	v_mov_b32_e32 v139, v138
	s_nop 1
	v_permlane16_swap_b32_e32 v138, v139
	s_and_saveexec_b64 s[64:65], vcc
	s_cbranch_execz .LBB0_1518
	v_add_f32_e32 v140, v138, v139
	s_lshl_b32 s66, s5, 2
	v_lshlrev_b64 v[138:139], 6, v[166:167]
	s_ashr_i32 s67, s66, 31
	v_lshl_add_u64 v[138:139], s[14:15], 0, v[138:139]
	v_lshl_add_u64 v[138:139], s[66:67], 2, v[138:139]
	s_lshl_b32 s66, s68, 2
	s_mov_b32 s67, s19
	v_lshl_add_u64 v[138:139], v[138:139], 0, s[66:67]
	global_store_dword v[138:139], v140, off
